# MLA-up K/V part: each wave's 32x64 result sub-tile staged through a private 4 KB LDS patch, leaves as 4 stores of 16 bytes per lane (8 rows x 128 contiguous bytes) instead of 32 two-byte-per-lane stor
# speedup vs baseline: 1.0053x; 1.0006x over previous
; DI unsigned pk2(float lo, float hi) { f32x2 v = {lo, hi}; b16x2 r = __builtin_convertvector(v, b16x2); return __builtin_bit_cast(unsigned, r); }
; DI void phase_mla_up(const Params& p, int layer, char* lds) {
;     ...
;           const int head = c0 >> 7, within = c0 & 127;
;           const size_t hrow = (size_t)(bq * 6 + head) * S + srow;
;           if (within < 64) {
;             u16* kp = KB + hrow * 96 + within + l32;
; #pragma unroll
;             for (int r = 0; r < 16; ++r) kp[((r & 3) + 8 * (r >> 2)) * 96] = (u16)(pk2(acc[r] * rv[r], 0.f) & 0xffffu);
;           } else {
;             u16* vp = VB + hrow * 64 + (within - 64) + l32;
; #pragma unroll
;             for (int r = 0; r < 16; ++r) vp[((r & 3) + 8 * (r >> 2)) * 64] = (u16)(pk2(acc[r] * rv[r], 0.f) & 0xffffu);
;           }
.LBB0_222:
	s_mov_b64 s[12:13], -1
	s_and_b64 vcc, exec, s[20:21]
	s_cbranch_vccz .LBB0_228
	v_ashrrev_i32_e32 v4, 7, v78
	v_add_u32_e32 v80, s28, v4
	v_ashrrev_i32_e32 v81, 31, v80
	v_lshlrev_b64 v[80:81], 13, v[80:81]
	v_or_b32_e32 v80, v80, v72
	s_and_saveexec_b64 s[12:13], s[6:7]
	s_xor_b64 s[12:13], exec, s[12:13]
	s_cbranch_execz .LBB0_225
	v_lshlrev_b64 v[80:81], 7, v[80:81]
	v_mul_f32_e32 v4, v95, v22
	v_mul_f32_e32 v238, v95, v6
	v_lshl_add_u64 v[80:81], v[66:67], 0, v[80:81]
	v_and_b32_e32 v124, 63, v184
	v_lshrrev_b32_e32 v125, 6, v184
	v_lshlrev_b32_e32 v125, 12, v125
	v_add_u32_e32 v125, 106496, v125
	v_lshl_add_u32 v144, v124, 1, v125
	v_lshl_add_u32 v145, v124, 4, v125
	v_lshrrev_b32_e32 v125, 3, v124
	v_mul_u32_u24_e32 v125, 128, v125
	v_and_b32_e32 v126, 7, v124
	v_lshl_add_u32 v125, v126, 4, v125
	v_lshrrev_b32_e32 v126, 5, v124
	v_mul_u32_u24_e32 v126, 512, v126
	v_sub_u32_e32 v125, v125, v126
	v_and_b32_e32 v126, 31, v124
	v_lshlrev_b32_e32 v126, 1, v126
	v_sub_u32_e32 v124, v125, v126
	v_add_u32_e32 v124, -128, v124
	v_ashrrev_i32_e32 v125, 31, v124
	v_lshl_add_u64 v[116:117], v[80:81], 0, v[124:125]
	v_cvt_pk_bf16_f32 v4, v4, s0
	v_cvt_pk_bf16_f32 v238, v238, s0
	s_nop 1
	v_permlane32_swap_b32_e32 v4, v238
	ds_write_b16 v144, v4
	ds_write_b16 v144, v238 offset:512
	v_mul_f32_e32 v4, v96, v23
	v_mul_f32_e32 v238, v96, v7
	v_cvt_pk_bf16_f32 v4, v4, s0
	v_cvt_pk_bf16_f32 v238, v238, s0
	s_nop 1
	v_permlane32_swap_b32_e32 v4, v238
	ds_write_b16 v144, v4 offset:128
	ds_write_b16 v144, v238 offset:640
	v_mul_f32_e32 v4, v97, v24
	v_mul_f32_e32 v238, v97, v8
	v_cvt_pk_bf16_f32 v4, v4, s0
	v_cvt_pk_bf16_f32 v238, v238, s0
	s_nop 1
	v_permlane32_swap_b32_e32 v4, v238
	ds_write_b16 v144, v4 offset:256
	ds_write_b16 v144, v238 offset:768
	v_mul_f32_e32 v4, v98, v25
	v_mul_f32_e32 v238, v98, v9
	v_cvt_pk_bf16_f32 v4, v4, s0
	v_cvt_pk_bf16_f32 v238, v238, s0
	s_nop 1
	v_permlane32_swap_b32_e32 v4, v238
	ds_write_b16 v144, v4 offset:384
	ds_write_b16 v144, v238 offset:896
	v_mul_f32_e32 v4, v99, v26
	v_mul_f32_e32 v238, v99, v10
	v_cvt_pk_bf16_f32 v4, v4, s0
	v_cvt_pk_bf16_f32 v238, v238, s0
	s_nop 1
	v_permlane32_swap_b32_e32 v4, v238
	ds_write_b16 v144, v4 offset:1024
	ds_write_b16 v144, v238 offset:1536
	v_mul_f32_e32 v4, v100, v27
	v_mul_f32_e32 v238, v100, v11
	v_cvt_pk_bf16_f32 v4, v4, s0
	v_cvt_pk_bf16_f32 v238, v238, s0
	s_nop 1
	v_permlane32_swap_b32_e32 v4, v238
	ds_write_b16 v144, v4 offset:1152
	ds_write_b16 v144, v238 offset:1664
	v_mul_f32_e32 v4, v101, v28
	v_mul_f32_e32 v238, v101, v12
	v_cvt_pk_bf16_f32 v4, v4, s0
	v_cvt_pk_bf16_f32 v238, v238, s0
	s_nop 1
	v_permlane32_swap_b32_e32 v4, v238
	ds_write_b16 v144, v4 offset:1280
	ds_write_b16 v144, v238 offset:1792
	v_mul_f32_e32 v4, v102, v29
	v_mul_f32_e32 v238, v102, v13
	v_cvt_pk_bf16_f32 v4, v4, s0
	v_cvt_pk_bf16_f32 v238, v238, s0
	s_nop 1
	v_permlane32_swap_b32_e32 v4, v238
	ds_write_b16 v144, v4 offset:1408
	ds_write_b16 v144, v238 offset:1920
	v_mul_f32_e32 v4, v103, v30
	v_mul_f32_e32 v238, v103, v14
	v_cvt_pk_bf16_f32 v4, v4, s0
	v_cvt_pk_bf16_f32 v238, v238, s0
	s_nop 1
	v_permlane32_swap_b32_e32 v4, v238
	ds_write_b16 v144, v4 offset:2048
	ds_write_b16 v144, v238 offset:2560
	v_mul_f32_e32 v4, v104, v31
	v_mul_f32_e32 v238, v104, v15
	v_cvt_pk_bf16_f32 v4, v4, s0
	v_cvt_pk_bf16_f32 v238, v238, s0
	s_nop 1
	v_permlane32_swap_b32_e32 v4, v238
	ds_write_b16 v144, v4 offset:2176
	ds_write_b16 v144, v238 offset:2688
	v_mul_f32_e32 v4, v105, v32
	v_mul_f32_e32 v238, v105, v16
	v_cvt_pk_bf16_f32 v4, v4, s0
	v_cvt_pk_bf16_f32 v238, v238, s0
	s_nop 1
	v_permlane32_swap_b32_e32 v4, v238
	ds_write_b16 v144, v4 offset:2304
	ds_write_b16 v144, v238 offset:2816
	v_mul_f32_e32 v4, v106, v33
	v_mul_f32_e32 v238, v106, v17
	v_cvt_pk_bf16_f32 v4, v4, s0
	v_cvt_pk_bf16_f32 v238, v238, s0
	s_nop 1
	v_permlane32_swap_b32_e32 v4, v238
	ds_write_b16 v144, v4 offset:2432
	ds_write_b16 v144, v238 offset:2944
	v_mul_f32_e32 v4, v107, v34
	v_mul_f32_e32 v238, v107, v18
	v_cvt_pk_bf16_f32 v4, v4, s0
	v_cvt_pk_bf16_f32 v238, v238, s0
	s_nop 1
	v_permlane32_swap_b32_e32 v4, v238
	ds_write_b16 v144, v4 offset:3072
	ds_write_b16 v144, v238 offset:3584
	v_mul_f32_e32 v4, v108, v35
	v_mul_f32_e32 v238, v108, v19
	v_cvt_pk_bf16_f32 v4, v4, s0
	v_cvt_pk_bf16_f32 v238, v238, s0
	s_nop 1
	v_permlane32_swap_b32_e32 v4, v238
	ds_write_b16 v144, v4 offset:3200
	ds_write_b16 v144, v238 offset:3712
	v_mul_f32_e32 v4, v109, v36
	v_mul_f32_e32 v238, v109, v20
	v_cvt_pk_bf16_f32 v4, v4, s0
	v_cvt_pk_bf16_f32 v238, v238, s0
	s_nop 1
	v_permlane32_swap_b32_e32 v4, v238
	ds_write_b16 v144, v4 offset:3328
	ds_write_b16 v144, v238 offset:3840
	v_mul_f32_e32 v4, v110, v37
	v_mul_f32_e32 v238, v110, v21
	v_cvt_pk_bf16_f32 v4, v4, s0
	v_cvt_pk_bf16_f32 v238, v238, s0
	s_nop 1
	v_permlane32_swap_b32_e32 v4, v238
	ds_write_b16 v144, v4 offset:3456
	ds_write_b16 v144, v238 offset:3968
	s_waitcnt lgkmcnt(0)
	ds_read_b128 v[128:131], v145
	ds_read_b128 v[132:135], v145 offset:1024
	ds_read_b128 v[136:139], v145 offset:2048
	ds_read_b128 v[140:143], v145 offset:3072
	s_waitcnt lgkmcnt(3)
	global_store_dwordx4 v[116:117], v[128:131], off
	s_waitcnt lgkmcnt(2)
	global_store_dwordx4 v[116:117], v[132:135], off offset:1024
	s_waitcnt lgkmcnt(1)
	global_store_dwordx4 v[116:117], v[136:139], off offset:2048
	s_waitcnt lgkmcnt(0)
	global_store_dwordx4 v[116:117], v[140:143], off offset:3072
; DI unsigned pk2(float lo, float hi) { f32x2 v = {lo, hi}; b16x2 r = __builtin_convertvector(v, b16x2); return __builtin_bit_cast(unsigned, r); }
; DI void phase_mla_up(const Params& p, int layer, char* lds) {
;     ...
;           const int head = c0 >> 7, within = c0 & 127;
;           const size_t hrow = (size_t)(bq * 6 + head) * S + srow;
;           if (within < 64) {
;             u16* kp = KB + hrow * 96 + within + l32;
; #pragma unroll
;             for (int r = 0; r < 16; ++r) kp[((r & 3) + 8 * (r >> 2)) * 96] = (u16)(pk2(acc[r] * rv[r], 0.f) & 0xffffu);
;           } else {
;             u16* vp = VB + hrow * 64 + (within - 64) + l32;
; #pragma unroll
;             for (int r = 0; r < 16; ++r) vp[((r & 3) + 8 * (r >> 2)) * 64] = (u16)(pk2(acc[r] * rv[r], 0.f) & 0xffffu);
.LBB0_225:
	s_andn2_saveexec_b64 s[12:13], s[12:13]
	s_cbranch_execz .LBB0_227
	v_mad_u64_u32 v[112:113], s[54:55], v80, s33, v[60:61]
	v_mul_f32_e32 v4, v95, v22
	v_mul_f32_e32 v238, v95, v6
	v_mad_i32_i24 v113, v81, s33, v113
	v_and_b32_e32 v124, 63, v184
	v_lshrrev_b32_e32 v125, 6, v184
	v_lshlrev_b32_e32 v125, 12, v125
	v_add_u32_e32 v125, 106496, v125
	v_lshl_add_u32 v144, v124, 1, v125
	v_lshl_add_u32 v145, v124, 4, v125
	v_lshrrev_b32_e32 v125, 3, v124
	v_mul_u32_u24_e32 v125, 192, v125
	v_and_b32_e32 v126, 7, v124
	v_lshl_add_u32 v125, v126, 4, v125
	v_lshrrev_b32_e32 v126, 5, v124
	v_mul_u32_u24_e32 v126, 768, v126
	v_sub_u32_e32 v125, v125, v126
	v_and_b32_e32 v126, 31, v124
	v_lshlrev_b32_e32 v126, 1, v126
	v_sub_u32_e32 v124, v125, v126
	v_ashrrev_i32_e32 v125, 31, v124
	v_lshl_add_u64 v[116:117], v[112:113], 0, v[124:125]
	v_mov_b32_e32 v124, 3072
	v_mov_b32_e32 v125, 0
	v_lshl_add_u64 v[118:119], v[116:117], 0, v[124:125]
	v_cvt_pk_bf16_f32 v4, v4, s0
	v_cvt_pk_bf16_f32 v238, v238, s0
	s_nop 1
	v_permlane32_swap_b32_e32 v4, v238
	ds_write_b16 v144, v4
	ds_write_b16 v144, v238 offset:512
	v_mul_f32_e32 v4, v96, v23
	v_mul_f32_e32 v238, v96, v7
	v_cvt_pk_bf16_f32 v4, v4, s0
	v_cvt_pk_bf16_f32 v238, v238, s0
	s_nop 1
	v_permlane32_swap_b32_e32 v4, v238
	ds_write_b16 v144, v4 offset:128
	ds_write_b16 v144, v238 offset:640
	v_mul_f32_e32 v4, v97, v24
	v_mul_f32_e32 v238, v97, v8
	v_cvt_pk_bf16_f32 v4, v4, s0
	v_cvt_pk_bf16_f32 v238, v238, s0
	s_nop 1
	v_permlane32_swap_b32_e32 v4, v238
	ds_write_b16 v144, v4 offset:256
	ds_write_b16 v144, v238 offset:768
	v_mul_f32_e32 v4, v98, v25
	v_mul_f32_e32 v238, v98, v9
	v_cvt_pk_bf16_f32 v4, v4, s0
	v_cvt_pk_bf16_f32 v238, v238, s0
	s_nop 1
	v_permlane32_swap_b32_e32 v4, v238
	ds_write_b16 v144, v4 offset:384
	ds_write_b16 v144, v238 offset:896
	v_mul_f32_e32 v4, v99, v26
	v_mul_f32_e32 v238, v99, v10
	v_cvt_pk_bf16_f32 v4, v4, s0
	v_cvt_pk_bf16_f32 v238, v238, s0
	s_nop 1
	v_permlane32_swap_b32_e32 v4, v238
	ds_write_b16 v144, v4 offset:1024
	ds_write_b16 v144, v238 offset:1536
	v_mul_f32_e32 v4, v100, v27
	v_mul_f32_e32 v238, v100, v11
	v_cvt_pk_bf16_f32 v4, v4, s0
	v_cvt_pk_bf16_f32 v238, v238, s0
	s_nop 1
	v_permlane32_swap_b32_e32 v4, v238
	ds_write_b16 v144, v4 offset:1152
	ds_write_b16 v144, v238 offset:1664
	v_mul_f32_e32 v4, v101, v28
	v_mul_f32_e32 v238, v101, v12
	v_cvt_pk_bf16_f32 v4, v4, s0
	v_cvt_pk_bf16_f32 v238, v238, s0
	s_nop 1
	v_permlane32_swap_b32_e32 v4, v238
	ds_write_b16 v144, v4 offset:1280
	ds_write_b16 v144, v238 offset:1792
	v_mul_f32_e32 v4, v102, v29
	v_mul_f32_e32 v238, v102, v13
	v_cvt_pk_bf16_f32 v4, v4, s0
	v_cvt_pk_bf16_f32 v238, v238, s0
	s_nop 1
	v_permlane32_swap_b32_e32 v4, v238
	ds_write_b16 v144, v4 offset:1408
	ds_write_b16 v144, v238 offset:1920
	v_mul_f32_e32 v4, v103, v30
	v_mul_f32_e32 v238, v103, v14
	v_cvt_pk_bf16_f32 v4, v4, s0
	v_cvt_pk_bf16_f32 v238, v238, s0
	s_nop 1
	v_permlane32_swap_b32_e32 v4, v238
	ds_write_b16 v144, v4 offset:2048
	ds_write_b16 v144, v238 offset:2560
	v_mul_f32_e32 v4, v104, v31
	v_mul_f32_e32 v238, v104, v15
	v_cvt_pk_bf16_f32 v4, v4, s0
	v_cvt_pk_bf16_f32 v238, v238, s0
	s_nop 1
	v_permlane32_swap_b32_e32 v4, v238
	ds_write_b16 v144, v4 offset:2176
	ds_write_b16 v144, v238 offset:2688
	v_mul_f32_e32 v4, v105, v32
	v_mul_f32_e32 v238, v105, v16
	v_cvt_pk_bf16_f32 v4, v4, s0
	v_cvt_pk_bf16_f32 v238, v238, s0
	s_nop 1
	v_permlane32_swap_b32_e32 v4, v238
	ds_write_b16 v144, v4 offset:2304
	ds_write_b16 v144, v238 offset:2816
	v_mul_f32_e32 v4, v106, v33
	v_mul_f32_e32 v238, v106, v17
	v_cvt_pk_bf16_f32 v4, v4, s0
	v_cvt_pk_bf16_f32 v238, v238, s0
	s_nop 1
	v_permlane32_swap_b32_e32 v4, v238
	ds_write_b16 v144, v4 offset:2432
	ds_write_b16 v144, v238 offset:2944
	v_mul_f32_e32 v4, v107, v34
	v_mul_f32_e32 v238, v107, v18
	v_cvt_pk_bf16_f32 v4, v4, s0
	s_nop 0
	v_cvt_pk_bf16_f32 v238, v238, s0
	s_nop 1
	v_permlane32_swap_b32_e32 v4, v238
	ds_write_b16 v144, v4 offset:3072
	ds_write_b16 v144, v238 offset:3584
	v_mul_f32_e32 v4, v108, v35
	v_mul_f32_e32 v238, v108, v19
	v_cvt_pk_bf16_f32 v4, v4, s0
	v_cvt_pk_bf16_f32 v238, v238, s0
	s_nop 1
	v_permlane32_swap_b32_e32 v4, v238
	ds_write_b16 v144, v4 offset:3200
	ds_write_b16 v144, v238 offset:3712
	v_mul_f32_e32 v4, v109, v36
	v_mul_f32_e32 v238, v109, v20
	v_cvt_pk_bf16_f32 v4, v4, s0
	v_cvt_pk_bf16_f32 v238, v238, s0
	s_nop 1
	v_permlane32_swap_b32_e32 v4, v238
	ds_write_b16 v144, v4 offset:3328
	ds_write_b16 v144, v238 offset:3840
	v_mul_f32_e32 v4, v110, v37
	v_mul_f32_e32 v238, v110, v21
	v_cvt_pk_bf16_f32 v4, v4, s0
	v_cvt_pk_bf16_f32 v238, v238, s0
	s_nop 1
	v_permlane32_swap_b32_e32 v4, v238
	ds_write_b16 v144, v4 offset:3456
	ds_write_b16 v144, v238 offset:3968
	s_waitcnt lgkmcnt(0)
	ds_read_b128 v[128:131], v145
	ds_read_b128 v[132:135], v145 offset:1024
	ds_read_b128 v[136:139], v145 offset:2048
	ds_read_b128 v[140:143], v145 offset:3072
	s_waitcnt lgkmcnt(3)
	global_store_dwordx4 v[116:117], v[128:131], off
	s_waitcnt lgkmcnt(2)
	global_store_dwordx4 v[116:117], v[132:135], off offset:1536
	s_waitcnt lgkmcnt(1)
	global_store_dwordx4 v[118:119], v[136:139], off
	s_waitcnt lgkmcnt(0)
	global_store_dwordx4 v[118:119], v[140:143], off offset:1536
